# weight f32->bf16 transposes not needed by the first GEMM are done by the workgroups that idle in the partial last round of GEMM 1 / split-K round of GEMM 2 instead of in the prologue
# speedup vs baseline: 1.0345x; 1.0061x over previous
; #define PG8_LAS __attribute__((address_space(3)))
; #define LAS __attribute__((address_space(3)))
; __device__ __forceinline__ unsigned xb_add(unsigned* p, unsigned v) { return __hip_atomic_fetch_add(p, v, __ATOMIC_RELAXED, __HIP_MEMORY_SCOPE_AGENT); }
; __device__ __forceinline__ unsigned xb_xcc_id() { return (unsigned)__builtin_amdgcn_s_getreg((3 << 11) | 20) & 0xFu; }
; __global__ void __launch_bounds__(512, 2) fox_fwd(Args args) {
;     extern __shared__ __attribute__((aligned(16))) unsigned char lds[];
;     cg::grid_group grid = cg::this_grid();
;     const int G = gridDim.x, bx = blockIdx.x;
;     constexpr int LDS_BARST = 131072 + 512;
;     if (threadIdx.x < 64) ((LAS unsigned*)((PG8_LAS unsigned char*)lds + 131072))[threadIdx.x] = 0u;
;     if (threadIdx.x < 2) ((LAS unsigned*)((PG8_LAS unsigned char*)lds + LDS_BARST))[threadIdx.x] = 0u;
;     __syncthreads();
;     if (threadIdx.x == 0 && args.ph_hi - args.ph_lo > 1) { unsigned* bar_ = (unsigned*)args.ws; (void)xb_add(&bar_[XB_XCNT(xb_xcc_id())], 1u); }
_Z7fox_fwd4Args:
	s_mov_b32 s99, 0
	s_mov_b32 s101, 0
	s_load_dwordx2 s[44:45], s[0:1], 0xb8
	s_mov_b64 s[54:55], s[0:1]
	s_add_u32 s6, s54, 0xc0
	v_and_b32_e32 v182, 0x3ff, v0
	s_addc_u32 s7, s55, 0
	v_cmp_gt_u32_e32 vcc, 64, v182
	v_lshl_add_u32 v1, v182, 2, 0
	s_and_saveexec_b64 s[4:5], vcc
	v_add_u32_e32 v2, 0x20000, v1
	v_mov_b32_e32 v3, 0
	ds_write_b32 v2, v3
	s_or_b64 exec, exec, s[4:5]
	s_load_dwordx2 s[48:49], s[54:55], 0xc0
	v_cmp_gt_u32_e32 vcc, 2, v182
	s_and_saveexec_b64 s[4:5], vcc
	v_add_u32_e32 v1, 0x20200, v1
	v_mov_b32_e32 v2, 0
	ds_write_b32 v1, v2
	s_or_b64 exec, exec, s[4:5]
	s_load_dword s0, s[54:55], 0xc8
	v_cmp_eq_u32_e64 s[8:9], 0, v182
	s_waitcnt lgkmcnt(0)
	s_barrier
	v_writelane_b32 v250, s0, 0
	s_sub_i32 s0, s45, s44
	s_cmp_gt_i32 s0, 1
	s_cselect_b64 s[4:5], -1, 0
	v_writelane_b32 v250, s8, 1
	s_and_b64 s[0:1], s[8:9], s[4:5]
	s_nop 0
	v_writelane_b32 v250, s9, 2
	s_and_saveexec_b64 s[8:9], s[0:1]
	s_cbranch_execz .LBB0_7
	s_mov_b64 s[10:11], exec
	v_mbcnt_lo_u32_b32 v1, s10, 0
	v_mbcnt_hi_u32_b32 v1, s11, v1
	v_cmp_eq_u32_e32 vcc, 0, v1
	s_getreg_b32 s0, hwreg(HW_REG_XCC_ID, 0, 4)
	s_and_b64 s[12:13], exec, vcc
	s_mov_b64 exec, s[12:13]
	s_cbranch_execz .LBB0_7
	s_load_dwordx2 s[12:13], s[54:55], 0xb0
	s_lshl_b32 s0, s0, 8
	s_and_b32 s0, s0, 0xf00
	s_bcnt1_i32_b64 s1, s[10:11]
	v_mov_b32_e32 v1, s0
	v_mov_b32_e32 v2, s1
	s_waitcnt lgkmcnt(0)
	global_atomic_add v1, v2, s[12:13] offset:1024

; __global__ void __launch_bounds__(512, 2) fox_fwd(Args args) {
;     ...
;         const int gw = bx * 8 + wave, NGW = G * 8;
;         constexpr int I_GU = (DM / 64) * (DFF / 32), I_DN = (DFF / 64) * (DM / 32), I_INA = (DM / 64) * (3 * FOXW / 32), I_INP = (DM / 64) * (POOLW / 32), I_O = (DM / 64) * (DM / 32), I_PL = 4 * (256 / 64) * (256 / 32);
;         constexpr int NITEMS = 4 * I_GU + 2 * I_DN + I_INA + I_INP + I_O + I_PL;
;         for (int it = gw; it < NITEMS; it += NGW) {
;             int r = it;
;             if (r < 4 * I_GU) {
;                 const int which = r / I_GU; r -= which * I_GU; const int nblk = DFF / 32, kb = r / nblk, nb = r % nblk, n0 = 32 * nb;
;                 const float* W = A_->in[which == 0 ? 7 : which == 1 ? 8 : which == 2 ? 17 : 18];
;                 bf16_t* WT = which < 2 ? Wgu1 : Wgu2; const int drow = (n0 >> 7) * 256 + (which & 1) * 128 + (n0 & 127);
;                 transpose_item(W + n0, DFF, WT, DM, drow, 64 * kb, scr, lane, which < 2 ? nullptr : A_->in[16]); continue; }
;             r -= 4 * I_GU;
;             if (r < 2 * I_DN) { const int which = r / I_DN; r -= which * I_DN; const int nblk = DM / 32, kb = r / nblk, nb = r % nblk;
;                 transpose_item(A_->in[which == 0 ? 9 : 19] + 32 * nb, DM, which == 0 ? Wd1 : Wd2, DFF, 32 * nb, 64 * kb, scr, lane); continue; }
;             r -= 2 * I_DN;
;             if (r < I_INA) { const int nblk = 3 * FOXW / 32, kb = r / nblk, nb = r % nblk; transpose_item(A_->in[11] + 32 * nb, INW, Win, DM, 32 * nb, 64 * kb, scr, lane, A_->in[10]); continue; }
;             r -= I_INA;
;             if (r < I_INP) { const int nblk = POOLW / 32, kb = r / nblk, nb = r % nblk; transpose_item(A_->in[11] + 3 * FOXW + NH + 32 * nb, INW, Win, DM, 3 * FOXW + 32 * nb, 64 * kb, scr, lane, A_->in[10]); continue; }
;             r -= I_INP;
;             if (r < I_O) { const int nblk = DM / 32, kb = r / nblk, nb = r % nblk;
;                 if (kb < 16) transpose_item(A_->in[15] + 32 * nb, DM, Wo, DM, 32 * nb, 64 * kb, scr, lane);
;                 else transpose_item(A_->in[15] + (size_t)FOXW * DM + 32 * nb, DM, (bf16_t*)(ws + WS_D), FOXW, 32 * nb, 64 * kb - FOXW, scr, lane);
;                 continue; }
;             r -= I_O;
;             { }
;         }
.Lp0_reenter:
	s_mov_b64 s[22:23], s[54:55]
	s_load_dwordx2 s[20:21], s[22:23], 0xb0
	s_load_dwordx4 s[8:11], s[22:23], 0x0
	v_mov_b32_e32 v33, v182
	s_waitcnt lgkmcnt(0)
	s_add_u32 s24, s20, 0x4400000
	v_readfirstlane_b32 s0, v33
	s_addc_u32 s25, s21, 0
	s_ashr_i32 s3, s0, 6
	s_lshl_b32 s0, s2, 3
	s_add_i32 s16, s3, s0
	s_lshl_b32 s18, s48, 3
	s_cmp_gt_i32 s16, 0x9c7f
	v_and_b32_e32 v32, 63, v33
	s_cbranch_scc1 .LBB0_96
	v_and_b32_e32 v1, 7, v33
	s_lshl_b32 s0, s3, 14
	v_mov_b32_e32 v35, 0
	v_lshlrev_b32_e32 v34, 4, v1
	s_add_i32 s4, s0, 0
	v_lshrrev_b32_e32 v37, 3, v32
	v_lshl_add_u64 v[2:3], s[20:21], 0, v[34:35]
	s_mov_b64 s[0:1], 0x28800000
	v_lshlrev_b32_e32 v0, 2, v1
	v_add_u32_e32 v4, s4, v34
	v_mul_u32_u24_e32 v5, 0x84, v37
	v_lshlrev_b32_e32 v36, 3, v1
	v_mul_u32_u24_e32 v1, 0x420, v1
	v_lshl_add_u64 v[38:39], v[2:3], 0, s[0:1]
	v_lshlrev_b32_e32 v6, 2, v37
	s_mov_b64 s[0:1], 0x5500000
	v_add3_u32 v51, s4, v1, v6
	v_lshl_add_u64 v[40:41], v[2:3], 0, s[0:1]
	s_lshl_b32 s0, s2, 8
	s_lshl_b32 s1, s3, 5
	s_lshl_b32 s4, s2, 4
	s_lshl_b32 s3, s3, 1
	v_add_u32_e32 v52, v4, v5
	s_mov_b32 s27, 0
	v_or_b32_e32 v48, 8, v37
	v_or_b32_e32 v49, 16, v37
	v_or_b32_e32 v50, 24, v37
	v_lshl_add_u64 v[42:43], s[24:25], 0, v[34:35]
	s_add_i32 s0, s0, s1
	s_lshl_b32 s1, s48, 8
	s_add_i32 s3, s4, s3
	s_lshl_b32 s17, s48, 4
	s_mov_b64 s[28:29], 0x800000
	v_add_u32_e32 v53, 0x420, v52
	v_add_u32_e32 v54, 0x428, v52
	v_add_u32_e32 v55, 0x840, v52
	v_add_u32_e32 v56, 0x848, v52
	v_add_u32_e32 v57, 0xc60, v52
	v_add_u32_e32 v58, 0xc68, v52
	v_add_u32_e32 v59, 0x1080, v52
	v_add_u32_e32 v60, 0x1088, v52
	v_add_u32_e32 v61, 0x14a0, v52
	v_add_u32_e32 v62, 0x14a8, v52
	v_add_u32_e32 v63, 0x18c0, v52
	v_add_u32_e32 v64, 0x18c8, v52
	v_add_u32_e32 v65, 0x1ce0, v52
	v_add_u32_e32 v66, 0x1ce8, v52
	s_mov_b32 s19, 0x10000
	s_mov_b32 s33, 0x20000
	s_mov_b32 s38, 0x30000
	s_mov_b32 s39, 0x40000
	s_mov_b32 s40, 0x50000
	s_mov_b32 s41, 0x60000
	s_mov_b32 s42, 0x70000
	s_mov_b64 s[30:31], 0x3020
	s_movk_i32 s43, 0x4020
	s_movk_i32 s44, 0x48
	s_mov_b32 s45, 0x2e00000
	s_movk_i32 s46, 0x5800
	s_mov_b32 s47, 0x200000
	v_lshlrev_b32_e32 v44, 2, v0
	s_mov_b32 s50, s16
	s_cmp_eq_u32 s99, 0
	s_cbranch_scc0 .Lp0_m1
	s_mov_b32 s100, 0x9c7f
	s_cmpk_eq_u32 s48, 0x100
	s_cbranch_scc0 .Lp0_go
	s_mov_b32 s101, 1
	s_movk_i32 s100, 0x2bff
	s_branch .Lp0_go
.Lp0_m1:
	s_cmp_eq_u32 s99, 1
	s_cbranch_scc0 .Lp0_m2
	s_add_u32 s50, s16, 0x5540
	s_movk_i32 s18, 0x540
	s_mov_b32 s100, 0x9bff
	s_branch .Lp0_strides
.Lp0_m2:
	s_add_u32 s50, s16, 0x2a00
	s_movk_i32 s18, 0x600
	s_movk_i32 s100, 0x57ff
.Lp0_strides:
	s_lshl_b32 s0, s50, 5
	s_lshl_b32 s3, s50, 1
	s_lshl_b32 s1, s18, 5
	s_lshl_b32 s17, s18, 1
.Lp0_go:
	s_branch .LBB0_24
.LBB0_22:
	s_and_b64 s[4:5], exec, s[34:35]
	s_waitcnt vmcnt(7)
	ds_write2_b32 v52, v0, v1 offset1:1
	ds_write2_b32 v52, v2, v3 offset0:2 offset1:3
	s_waitcnt vmcnt(6)
	ds_write2_b32 v53, v4, v5 offset1:1
	ds_write2_b32 v54, v6, v7 offset1:1
	s_waitcnt vmcnt(5)
	ds_write2_b32 v55, v8, v9 offset1:1
	ds_write2_b32 v56, v10, v11 offset1:1
	s_waitcnt vmcnt(4)
	ds_write2_b32 v57, v12, v13 offset1:1
	ds_write2_b32 v58, v14, v15 offset1:1
	s_waitcnt vmcnt(3)
	ds_write2_b32 v59, v16, v17 offset1:1
	ds_write2_b32 v60, v18, v19 offset1:1
	s_waitcnt vmcnt(2)
	ds_write2_b32 v61, v20, v21 offset1:1
	ds_write2_b32 v62, v22, v23 offset1:1
	s_waitcnt vmcnt(1)
	ds_write2_b32 v63, v24, v25 offset1:1
	ds_write2_b32 v64, v26, v27 offset1:1
	s_waitcnt vmcnt(0)
	ds_write2_b32 v65, v28, v29 offset1:1
	ds_write2_b32 v66, v30, v31 offset1:1
	s_cselect_b32 s4, s47, 0x5d00000
	s_waitcnt lgkmcnt(0)
	s_add_u32 s13, s20, s4
	ds_read2_b32 v[0:1], v51 offset1:33
	s_addc_u32 s34, s21, 0
	s_lshl_b32 s4, s26, 6
	s_lshl_b32 s5, s15, 7
	s_waitcnt lgkmcnt(0)
	v_cvt_pk_bf16_f32 v0, v0, v1
	ds_read2_b32 v[2:3], v51 offset0:66 offset1:99
	s_and_b32 s4, s4, 0xffffff00
	s_and_b32 s5, s5, 0x80
	s_or_b32 s4, s4, s5
	s_waitcnt lgkmcnt(0)
	v_cvt_pk_bf16_f32 v1, v2, v3
	ds_read2_b32 v[2:3], v51 offset0:132 offset1:165
	s_and_b32 s5, s12, 0x60
	s_ashr_i32 s15, s14, 31
	s_or_b32 s12, s4, s5
	s_lshl_b64 s[4:5], s[14:15], 1
	s_waitcnt lgkmcnt(0)
	v_cvt_pk_bf16_f32 v2, v2, v3
	ds_read2_b32 v[4:5], v51 offset0:198 offset1:231
	s_add_u32 s4, s13, s4
	s_waitcnt lgkmcnt(0)
	v_cvt_pk_bf16_f32 v3, v4, v5
	v_or_b32_e32 v4, s12, v37
	s_addc_u32 s5, s34, s5
	v_lshlrev_b32_e32 v34, 1, v36
	v_ashrrev_i32_e32 v5, 31, v4
	v_lshl_add_u64 v[6:7], s[4:5], 0, v[34:35]
	v_lshlrev_b64 v[4:5], 12, v[4:5]
	v_lshl_add_u64 v[4:5], v[6:7], 0, v[4:5]
	ds_read2_b32 v[8:9], v51 offset0:8 offset1:41
	global_store_dwordx4 v[4:5], v[0:3], off
	s_waitcnt lgkmcnt(0)
	s_nop 0
	v_cvt_pk_bf16_f32 v0, v8, v9
	ds_read2_b32 v[2:3], v51 offset0:74 offset1:107
	s_waitcnt lgkmcnt(0)
	v_cvt_pk_bf16_f32 v1, v2, v3
	ds_read2_b32 v[2:3], v51 offset0:140 offset1:173
	s_waitcnt lgkmcnt(0)
	v_cvt_pk_bf16_f32 v2, v2, v3
	ds_read2_b32 v[4:5], v51 offset0:206 offset1:239
	s_waitcnt lgkmcnt(0)
	v_cvt_pk_bf16_f32 v3, v4, v5
	v_or_b32_e32 v4, s12, v48
	v_ashrrev_i32_e32 v5, 31, v4
	v_lshlrev_b64 v[4:5], 12, v[4:5]
	v_lshl_add_u64 v[4:5], v[6:7], 0, v[4:5]
	ds_read2_b32 v[8:9], v51 offset0:16 offset1:49
	global_store_dwordx4 v[4:5], v[0:3], off
	s_waitcnt lgkmcnt(0)
	s_nop 0
	v_cvt_pk_bf16_f32 v0, v8, v9
	ds_read2_b32 v[2:3], v51 offset0:82 offset1:115
	s_waitcnt lgkmcnt(0)
	v_cvt_pk_bf16_f32 v1, v2, v3
	ds_read2_b32 v[2:3], v51 offset0:148 offset1:181
	s_waitcnt lgkmcnt(0)
	v_cvt_pk_bf16_f32 v2, v2, v3
	ds_read2_b32 v[4:5], v51 offset0:214 offset1:247
	s_waitcnt lgkmcnt(0)
	v_cvt_pk_bf16_f32 v3, v4, v5
	v_or_b32_e32 v4, s12, v49
	v_ashrrev_i32_e32 v5, 31, v4
	v_lshlrev_b64 v[4:5], 12, v[4:5]
	v_lshl_add_u64 v[4:5], v[6:7], 0, v[4:5]
	ds_read2_b32 v[8:9], v51 offset0:24 offset1:57
	global_store_dwordx4 v[4:5], v[0:3], off
	s_waitcnt lgkmcnt(0)
	s_nop 0
	v_cvt_pk_bf16_f32 v0, v8, v9
	ds_read2_b32 v[2:3], v51 offset0:90 offset1:123
	s_waitcnt lgkmcnt(0)
	v_cvt_pk_bf16_f32 v1, v2, v3
	ds_read2_b32 v[2:3], v51 offset0:156 offset1:189
	v_or_b32_e32 v8, s12, v50
	s_waitcnt lgkmcnt(0)
	v_cvt_pk_bf16_f32 v2, v2, v3
	ds_read2_b32 v[4:5], v51 offset0:222 offset1:255
	v_ashrrev_i32_e32 v9, 31, v8
	s_waitcnt lgkmcnt(0)
	v_cvt_pk_bf16_f32 v3, v4, v5
	v_lshlrev_b64 v[4:5], 12, v[8:9]
	v_lshl_add_u64 v[4:5], v[6:7], 0, v[4:5]
	global_store_dwordx4 v[4:5], v[0:3], off
	s_waitcnt lgkmcnt(0)
.LBB0_23:
	s_add_i32 s50, s50, s18
	s_add_i32 s0, s0, s1
	s_add_i32 s3, s3, s17
	s_cmp_gt_i32 s50, s100
	s_cbranch_scc1 .LBB0_96

; __device__ __forceinline__ unsigned f2bf(float f) { unsigned u = __builtin_bit_cast(unsigned, f); return (u + 0x7fffu + ((u >> 16) & 1u)) >> 16; }
; __global__ void __launch_bounds__(512, 2) fox_fwd(Args args) {
;     ...
;         for (int i = bx * 512 + tid; i < NH * DM; i += G * 512) { const int j = i / DM, k = i % DM; Win[(size_t)(4 * FOXW + j) * DM + k] = (bf16_t)f2bf(A_->in[11][(size_t)k * INW + 3 * FOXW + j] * A_->in[10][k]); }
.LBB0_96:
	s_cmp_eq_u32 s99, 1
	s_cbranch_scc1 .Lp0_ret1
	s_cmp_eq_u32 s99, 2
	s_cbranch_scc1 .Lp0_ret2
	v_lshl_add_u32 v4, s2, 9, v33
	s_movk_i32 s1, 0x4000
	v_cmp_gt_i32_e32 vcc, s1, v4
	s_and_saveexec_b64 s[26:27], vcc
	s_cbranch_execz .LBB0_104
	s_lshl_b32 s0, s48, 9
	v_cvt_f32_u32_e32 v0, s0
	v_add_u32_e32 v5, s0, v4
	v_mov_b32_e32 v1, s0
	v_cmp_gt_i32_e32 vcc, s1, v5
	v_rcp_iflag_f32_e32 v0, v0
	s_sub_i32 s3, 0, s0
	v_max_i32_e32 v2, 0x4000, v5
	v_addc_co_u32_e64 v1, s[4:5], v4, v1, vcc
	v_mul_f32_e32 v0, 0x4f7ffffe, v0
	v_cvt_u32_f32_e32 v0, v0
	v_sub_u32_e32 v1, v2, v1
	s_load_dwordx4 s[12:15], s[22:23], 0x50
	s_mov_b64 s[28:29], -1
	v_mul_lo_u32 v2, s3, v0
	v_mul_hi_u32 v2, v0, v2
	v_add_u32_e32 v0, v0, v2
	v_mul_hi_u32 v0, v1, v0
	v_mul_lo_u32 v2, v0, s0
	v_sub_u32_e32 v1, v1, v2
	v_add_u32_e32 v2, 1, v0
	v_cmp_le_u32_e64 s[4:5], s0, v1
	s_nop 1
	v_cndmask_b32_e64 v0, v0, v2, s[4:5]
	v_subrev_u32_e32 v2, s0, v1
	v_cndmask_b32_e64 v1, v1, v2, s[4:5]
	v_add_u32_e32 v2, 1, v0
	v_cmp_le_u32_e64 s[4:5], s0, v1
	s_nop 1
	v_cndmask_b32_e64 v0, v0, v2, s[4:5]
	v_addc_co_u32_e32 v6, vcc, 1, v0, vcc
	v_cmp_lt_u32_e32 vcc, 1, v6
	v_mov_b32_e32 v0, v4
	s_and_saveexec_b64 s[4:5], vcc
	s_cbranch_execz .LBB0_101
	v_and_b32_e32 v7, -2, v6
	s_lshl_b32 s1, s48, 10
	s_mov_b32 s3, s1
	s_mov_b64 s[28:29], 0
	s_movk_i32 s17, 0x4020
	s_waitcnt lgkmcnt(0)
	v_mov_b64_e32 v[0:1], s[14:15]
	s_movk_i32 s19, 0x3000
	s_movk_i32 s30, 0x7fff
	s_mov_b32 s31, 0x1000000
	v_mov_b32_e32 v8, 1
	v_mov_b32_e32 v9, v7
	v_mov_b64_e32 v[2:3], v[4:5]

; __device__ __forceinline__ unsigned xb_ld(unsigned* p)              { return __hip_atomic_load(p, __ATOMIC_RELAXED, __HIP_MEMORY_SCOPE_AGENT); }
; __device__ __forceinline__ unsigned xb_add(unsigned* p, unsigned v) { return __hip_atomic_fetch_add(p, v, __ATOMIC_RELAXED, __HIP_MEMORY_SCOPE_AGENT); }
; __device__ __forceinline__ unsigned xb_xcc_id() { return (unsigned)__builtin_amdgcn_s_getreg((3 << 11) | 20) & 0xFu; }
; #define XB_SPIN(cond, bar) do { unsigned _sp = 0; while (cond) { __builtin_amdgcn_s_sleep(1); \
;     if ((++_sp & 255u) == 0u) { if (xb_ld(&(bar)[XB_TMO])) break; if (_sp > XB_SPIN_CAP) { atomicAdd(&(bar)[XB_TMO], 1u); break; } } } } while (0)
; __device__ __forceinline__ void xcd_barrier(unsigned* bar, volatile __attribute__((address_space(3))) unsigned* st) {
;     asm volatile("s_waitcnt vmcnt(0)" ::: "memory");
;     __syncthreads();
;     if (threadIdx.x == 0) {
;         const unsigned x = xb_xcc_id();
;         __builtin_amdgcn_s_waitcnt(0);
;         unsigned nloc = st[0], nx = st[1];
;         if (nloc == 0u) { xcd_barrier_complete(bar, x, nloc, nx); st[0] = nloc; st[1] = nx; }
;         const unsigned old = xb_add(&bar[XB_XSUB(x)], 1u);
;         const unsigned gen = old / nloc;
;         if (old + 1u == (gen + 1u) * nloc) {
;             __builtin_amdgcn_fence(__ATOMIC_RELEASE, "agent");
;             asm volatile("s_waitcnt vmcnt(0)" ::: "memory");
;             const unsigned og = xb_add(&bar[XB_TOP], 1u);
;             const unsigned tg = og / nx;
;             if (og + 1u == (tg + 1u) * nx) xb_add(&bar[XB_TOPGEN], 1u);
;             else XB_SPIN(xb_ld(&bar[XB_TOPGEN]) == tg, bar);
;             __builtin_amdgcn_fence(__ATOMIC_ACQUIRE, "agent");
;             xb_add(&bar[XB_XGEN(x)], 1u);
;             asm volatile("s_waitcnt vmcnt(0)" ::: "memory");
;         } else {
;             XB_SPIN(xb_ld(&bar[XB_XGEN(x)]) == gen, bar);
;             __builtin_amdgcn_fence(__ATOMIC_ACQUIRE, "agent");
;             asm volatile("s_waitcnt vmcnt(0)" ::: "memory");
;         }
;     }
;     __syncthreads();
; }
; __global__ void __launch_bounds__(512, 2) fox_fwd(Args args) {
;     ...
;     if (IN(1)) { PTRS TIDS pg8::Gemm g{ABUF, Wgu1, MTOT, 2 * DFF, DM, DM, 0}; pg8::StaticOrder S; S.init(MTOT, 2 * DFF, DM, G, bx, 0, nullptr, nullptr);
;         pg8::EpiGU E{HB, nullptr}; pg8::gemm_phase(lds3, g, S, E); }
;     SEAM(1);
.LBB0_214:
	s_waitcnt vmcnt(0)
	v_readlane_b32 s54, v250, 3
	v_readlane_b32 s44, v250, 5
	v_readlane_b32 s55, v250, 4
	v_readlane_b32 s45, v250, 6
	s_barrier
	s_cmp_eq_u32 s101, 1
	s_cbranch_scc0 .Lp0_skip1
	s_cmp_lt_u32 s2, 0x58
	s_cbranch_scc1 .Lp0_skip1
	s_mov_b32 s99, 1
	s_branch .Lp0_reenter
.Lp0_ret1:
	s_mov_b32 s99, 0
	v_readlane_b32 s54, v250, 3
	v_readlane_b32 s44, v250, 5
	v_readlane_b32 s55, v250, 4
	v_readlane_b32 s45, v250, 6
	s_mov_b64 s[4:5], -1
	s_nop 3
.Lp0_skip1:
.LBB0_215:
	s_cmp_gt_i32 s45, 2
	s_cselect_b64 s[6:7], -1, 0
	s_and_b64 s[0:1], s[4:5], s[6:7]
	s_andn2_b64 vcc, exec, s[0:1]
	s_cbranch_vccnz .LBB0_269
	s_mov_b64 s[8:9], s[54:55]
	s_waitcnt vmcnt(0)
	s_waitcnt vmcnt(0) lgkmcnt(0)
	s_barrier
	s_mov_b64 s[4:5], exec
	v_readlane_b32 s0, v250, 1
	v_readlane_b32 s1, v250, 2
	s_and_b64 s[0:1], s[4:5], s[0:1]
	s_mov_b64 exec, s[0:1]
	s_cbranch_execz .LBB0_268
	s_add_i32 s1, 0, 0x20200
	v_mov_b32_e32 v0, s1
	s_load_dwordx2 s[8:9], s[8:9], 0xb0
	s_getreg_b32 s0, hwreg(HW_REG_XCC_ID, 0, 4)
	s_waitcnt vmcnt(0) expcnt(0) lgkmcnt(0)
	ds_read_b32 v2, v0
	s_add_i32 s1, 0, 0x20204
	v_mov_b32_e32 v0, s1
	ds_read_b32 v0, v0
	s_and_b32 s0, s0, 15
	s_waitcnt lgkmcnt(1)
	v_cmp_ne_u32_e32 vcc, 0, v2
	s_cbranch_vccnz .LBB0_232
	s_add_u32 s10, s8, 0x1000
	s_addc_u32 s11, s9, 0
	s_add_u32 s12, s8, 0x1100
	s_addc_u32 s13, s9, 0
	s_add_u32 s14, s8, 0x1200
	v_readlane_b32 s1, v250, 0
	s_addc_u32 s15, s9, 0
	s_mul_i32 s1, s49, s1
	s_add_u32 s16, s8, 0x1300
	s_mul_i32 s1, s1, s48
	s_addc_u32 s17, s9, 0
	s_mov_b32 s3, 1
	v_mov_b32_e32 v16, 0
	s_branch .LBB0_220

; __device__ __forceinline__ unsigned xb_ld(unsigned* p)              { return __hip_atomic_load(p, __ATOMIC_RELAXED, __HIP_MEMORY_SCOPE_AGENT); }
; __device__ __forceinline__ unsigned xb_add(unsigned* p, unsigned v) { return __hip_atomic_fetch_add(p, v, __ATOMIC_RELAXED, __HIP_MEMORY_SCOPE_AGENT); }
; __device__ __forceinline__ unsigned xb_xcc_id() { return (unsigned)__builtin_amdgcn_s_getreg((3 << 11) | 20) & 0xFu; }
; #define XB_SPIN(cond, bar) do { unsigned _sp = 0; while (cond) { __builtin_amdgcn_s_sleep(1); \
;     if ((++_sp & 255u) == 0u) { if (xb_ld(&(bar)[XB_TMO])) break; if (_sp > XB_SPIN_CAP) { atomicAdd(&(bar)[XB_TMO], 1u); break; } } } } while (0)
; __device__ __forceinline__ void xcd_barrier(unsigned* bar, volatile __attribute__((address_space(3))) unsigned* st) {
;     asm volatile("s_waitcnt vmcnt(0)" ::: "memory");
;     __syncthreads();
;     if (threadIdx.x == 0) {
;         const unsigned x = xb_xcc_id();
;         __builtin_amdgcn_s_waitcnt(0);
;         unsigned nloc = st[0], nx = st[1];
;         if (nloc == 0u) { xcd_barrier_complete(bar, x, nloc, nx); st[0] = nloc; st[1] = nx; }
;         const unsigned old = xb_add(&bar[XB_XSUB(x)], 1u);
;         const unsigned gen = old / nloc;
;         if (old + 1u == (gen + 1u) * nloc) {
;             __builtin_amdgcn_fence(__ATOMIC_RELEASE, "agent");
;             asm volatile("s_waitcnt vmcnt(0)" ::: "memory");
;             const unsigned og = xb_add(&bar[XB_TOP], 1u);
;             const unsigned tg = og / nx;
;             if (og + 1u == (tg + 1u) * nx) xb_add(&bar[XB_TOPGEN], 1u);
;             else XB_SPIN(xb_ld(&bar[XB_TOPGEN]) == tg, bar);
;             __builtin_amdgcn_fence(__ATOMIC_ACQUIRE, "agent");
;             xb_add(&bar[XB_XGEN(x)], 1u);
;             asm volatile("s_waitcnt vmcnt(0)" ::: "memory");
;         } else {
;             XB_SPIN(xb_ld(&bar[XB_XGEN(x)]) == gen, bar);
;             __builtin_amdgcn_fence(__ATOMIC_ACQUIRE, "agent");
;             asm volatile("s_waitcnt vmcnt(0)" ::: "memory");
;         }
;     }
;     __syncthreads();
; }
; __global__ void __launch_bounds__(512, 2) fox_fwd(Args args) {
;     ...
;     if (IN(2)) { PTRS TIDS pg8::Gemm g{HB, Wd1, MTOT, DM, DFF, DFF, 0}; pg8::StaticOrder S; S.init(MTOT, DM, DFF, G, bx, 0, SPL, SPC);
;         pg8::EpiRes E{x_prompt, x_sample, nullptr, 0.5f, ABUF, rowss1}; pg8::gemm_phase(lds3, g, S, E); }
;     SEAM(2);
.LBB0_367:
	s_waitcnt vmcnt(0)
	v_readlane_b32 s54, v250, 3
	v_readlane_b32 s44, v250, 5
	v_readlane_b32 s55, v250, 4
	v_readlane_b32 s45, v250, 6
	s_barrier
	s_cmp_eq_u32 s101, 1
	s_cbranch_scc0 .Lp0_skip2
	s_cmp_lt_u32 s2, 0x40
	s_cbranch_scc1 .Lp0_skip2
	s_mov_b32 s99, 2
	s_branch .Lp0_reenter
.Lp0_ret2:
	s_mov_b32 s99, 0
	v_readlane_b32 s54, v250, 3
	v_readlane_b32 s44, v250, 5
	v_readlane_b32 s55, v250, 4
	v_readlane_b32 s45, v250, 6
	s_mov_b64 s[10:11], -1
	s_nop 3
.Lp0_skip2:
.LBB0_368:
	s_cmp_gt_i32 s45, 3
	s_cselect_b64 s[4:5], -1, 0
	s_and_b64 s[0:1], s[10:11], s[4:5]
	s_andn2_b64 vcc, exec, s[0:1]
	s_cbranch_vccnz .LBB0_427
	s_mov_b64 s[8:9], s[54:55]
	s_waitcnt vmcnt(0)
	s_waitcnt vmcnt(0) lgkmcnt(0)
	s_barrier
	s_mov_b64 s[6:7], exec
	v_readlane_b32 s0, v250, 1
	v_readlane_b32 s1, v250, 2
	s_and_b64 s[0:1], s[6:7], s[0:1]
	s_mov_b64 exec, s[0:1]
	s_cbranch_execz .LBB0_426
	s_add_i32 s1, 0, 0x20200
	v_mov_b32_e32 v0, s1
	s_load_dwordx2 s[8:9], s[8:9], 0xb0
	s_getreg_b32 s0, hwreg(HW_REG_XCC_ID, 0, 4)
	s_waitcnt vmcnt(0) expcnt(0) lgkmcnt(0)
	ds_read_b32 v2, v0
	s_add_i32 s1, 0, 0x20204
	v_mov_b32_e32 v0, s1
	ds_read_b32 v0, v0
	s_and_b32 s0, s0, 15
	s_waitcnt lgkmcnt(1)
	v_cmp_ne_u32_e32 vcc, 0, v2
	s_cbranch_vccnz .LBB0_385
	s_add_u32 s10, s8, 0x1000
	s_addc_u32 s11, s9, 0
	s_add_u32 s12, s8, 0x1100
	s_addc_u32 s13, s9, 0
	s_add_u32 s14, s8, 0x1200
	v_readlane_b32 s1, v250, 0
	s_addc_u32 s15, s9, 0
	s_mul_i32 s1, s49, s1
	s_add_u32 s16, s8, 0x1300
	s_mul_i32 s1, s1, s48
	s_addc_u32 s17, s9, 0
	s_mov_b32 s3, 1
	v_mov_b32_e32 v16, 0
	s_branch .LBB0_373

; __global__ void __launch_bounds__(512, 2) fox_fwd(Args args) {
	.amdhsa_kernel _Z7fox_fwd4Args
		.amdhsa_group_segment_fixed_size 0
		.amdhsa_private_segment_fixed_size 0
		.amdhsa_kernarg_size 448
		.amdhsa_user_sgpr_count 2
		.amdhsa_user_sgpr_dispatch_ptr 0
		.amdhsa_user_sgpr_queue_ptr 0
		.amdhsa_user_sgpr_kernarg_segment_ptr 1
		.amdhsa_user_sgpr_dispatch_id 0
		.amdhsa_user_sgpr_kernarg_preload_length 0
		.amdhsa_user_sgpr_kernarg_preload_offset 0
		.amdhsa_user_sgpr_private_segment_size 0
		.amdhsa_uses_dynamic_stack 0
		.amdhsa_enable_private_segment 0
		.amdhsa_system_sgpr_workgroup_id_x 1
		.amdhsa_system_sgpr_workgroup_id_y 0
		.amdhsa_system_sgpr_workgroup_id_z 0
		.amdhsa_system_sgpr_workgroup_info 0
		.amdhsa_system_vgpr_workitem_id 2
		.amdhsa_next_free_vgpr 256
		.amdhsa_next_free_sgpr 102
		.amdhsa_accum_offset 256
		.amdhsa_reserve_vcc 1
		.amdhsa_float_round_mode_32 0
		.amdhsa_float_round_mode_16_64 0
		.amdhsa_float_denorm_mode_32 3
		.amdhsa_float_denorm_mode_16_64 3
		.amdhsa_dx10_clamp 1
		.amdhsa_ieee_mode 1
		.amdhsa_fp16_overflow 0
		.amdhsa_tg_split 0
		.amdhsa_exception_fp_ieee_invalid_op 0
		.amdhsa_exception_fp_denorm_src 0
		.amdhsa_exception_fp_ieee_div_zero 0
		.amdhsa_exception_fp_ieee_overflow 0
		.amdhsa_exception_fp_ieee_underflow 0
		.amdhsa_exception_fp_ieee_inexact 0
		.amdhsa_exception_int_div_zero 0
	.end_amdhsa_kernel

amdhsa.kernels:
  - .agpr_count:     0
    .args:
      - .offset:         0
        .size:           192
        .value_kind:     by_value
      - .offset:         192
        .size:           4
        .value_kind:     hidden_block_count_x
      - .offset:         196
        .size:           4
        .value_kind:     hidden_block_count_y
      - .offset:         200
        .size:           4
        .value_kind:     hidden_block_count_z
      - .offset:         204
        .size:           2
        .value_kind:     hidden_group_size_x
      - .offset:         206
        .size:           2
        .value_kind:     hidden_group_size_y
      - .offset:         208
        .size:           2
        .value_kind:     hidden_group_size_z
      - .offset:         210
        .size:           2
        .value_kind:     hidden_remainder_x
      - .offset:         212
        .size:           2
        .value_kind:     hidden_remainder_y
      - .offset:         214
        .size:           2
        .value_kind:     hidden_remainder_z
      - .offset:         232
        .size:           8
        .value_kind:     hidden_global_offset_x
      - .offset:         240
        .size:           8
        .value_kind:     hidden_global_offset_y
      - .offset:         248
        .size:           8
        .value_kind:     hidden_global_offset_z
      - .offset:         256
        .size:           2
        .value_kind:     hidden_grid_dims
      - .offset:         280
        .size:           8
        .value_kind:     hidden_multigrid_sync_arg
      - .offset:         312
        .size:           4
        .value_kind:     hidden_dynamic_lds_size
    .group_segment_fixed_size: 0
    .kernarg_segment_align: 8
    .kernarg_segment_size: 448
    .language:       OpenCL C
    .language_version:
      - 2
      - 0
    .max_flat_workgroup_size: 512
    .name:           _Z7fox_fwd4Args
    .private_segment_fixed_size: 0
    .sgpr_count:     108
    .sgpr_spill_count: 16
    .symbol:         _Z7fox_fwd4Args.kd
    .uniform_work_group_size: 1
    .uses_dynamic_stack: false
    .vgpr_count:     256
    .vgpr_spill_count: 0
    .wavefront_size: 64
